# key loops: hazard s_nop removed by finishing the first score tile four MFMAs before the segment end (pass128) and relying on tile order (mixer B); bit-identical
# speedup vs baseline: 1.0740x; 1.0039x over previous
; __device__ __forceinline__ unsigned cvtpk(float lo, float hi) { const f32x2_t v = {lo, hi}; const bf16x2_t b = __builtin_convertvector(v, bf16x2_t); return __builtin_bit_cast(unsigned, b); }
; __device__ __forceinline__ void attn_pass2b(f32x16 (&o)[2][2], const bf16_t* qrow0, const bf16_t* Kb, const bf16_t* Vtb, int ka, int kb, LAS unsigned char* lds) {
;     ...
;         bf16x8 pk[2][4];
; #pragma unroll
;         for (int rb = 0; rb < 2; ++rb) {
;             f32x16& p0 = p[rb][0]; f32x16& p1 = p[rb][1];
;             float rs0 = 0.f, rs1 = 0.f;
; #pragma unroll
;             for (int r = 0; r < 16; ++r) { p0[r] = __builtin_amdgcn_exp2f(p0[r]); p1[r] = __builtin_amdgcn_exp2f(p1[r]); rs0 += p0[r]; rs1 += p1[r]; }
;             lrun[rb] += rs0 + rs1;
;             u32x4 w;
;             w.x = cvtpk(p0[0], p0[1]); w.y = cvtpk(p0[2], p0[3]); w.z = cvtpk(p0[4], p0[5]); w.w = cvtpk(p0[6], p0[7]); pk[rb][0] = __builtin_bit_cast(bf16x8, w);
;             w.x = cvtpk(p0[8], p0[9]); w.y = cvtpk(p0[10], p0[11]); w.z = cvtpk(p0[12], p0[13]); w.w = cvtpk(p0[14], p0[15]); pk[rb][1] = __builtin_bit_cast(bf16x8, w);
;             w.x = cvtpk(p1[0], p1[1]); w.y = cvtpk(p1[2], p1[3]); w.z = cvtpk(p1[4], p1[5]); w.w = cvtpk(p1[6], p1[7]); pk[rb][2] = __builtin_bit_cast(bf16x8, w);
;             w.x = cvtpk(p1[8], p1[9]); w.y = cvtpk(p1[10], p1[11]); w.z = cvtpk(p1[12], p1[13]); w.w = cvtpk(p1[14], p1[15]); pk[rb][3] = __builtin_bit_cast(bf16x8, w);
;         }
.Lpb_Y:
	s_setprio 0
	s_cmp_eq_u32 s3, 0
	s_cbranch_scc1 .Lpb_slow
	v_exp_f32_e32 v172, v128
	v_exp_f32_e32 v173, v129
	v_exp_f32_e32 v174, v130
	v_exp_f32_e32 v175, v131
	v_exp_f32_e32 v176, v132
	v_exp_f32_e32 v177, v133
	v_exp_f32_e32 v178, v134
	v_exp_f32_e32 v179, v135
	v_exp_f32_e32 v180, v136
	v_exp_f32_e32 v181, v137
	v_exp_f32_e32 v182, v138
	v_exp_f32_e32 v183, v139
	v_exp_f32_e32 v188, v140
	v_exp_f32_e32 v189, v141
	v_exp_f32_e32 v190, v142
	v_exp_f32_e32 v191, v143
	v_cvt_pk_bf16_f32 v222, v172, v173
	v_add_f32_e32 v2, v172, v174
	v_add_f32_e32 v6, v173, v175
	v_cvt_pk_bf16_f32 v223, v174, v175
	v_cvt_pk_bf16_f32 v224, v176, v177
	v_add_f32_e32 v2, v176, v2
	v_add_f32_e32 v6, v177, v6
	v_cvt_pk_bf16_f32 v225, v178, v179
	v_add_f32_e32 v2, v178, v2
	v_add_f32_e32 v6, v179, v6
	v_cvt_pk_bf16_f32 v226, v180, v181
	v_add_f32_e32 v2, v180, v2
	v_add_f32_e32 v6, v181, v6
	v_cvt_pk_bf16_f32 v227, v182, v183
	v_add_f32_e32 v2, v182, v2
	v_add_f32_e32 v6, v183, v6
	v_cvt_pk_bf16_f32 v228, v188, v189
	v_add_f32_e32 v2, v188, v2
	v_add_f32_e32 v6, v189, v6
	v_cvt_pk_bf16_f32 v229, v190, v191
	v_add_f32_e32 v2, v190, v2
	v_add_f32_e32 v6, v191, v6
	v_exp_f32_e32 v192, v144
	v_exp_f32_e32 v193, v145
	v_exp_f32_e32 v194, v146
	v_exp_f32_e32 v195, v147
	v_exp_f32_e32 v196, v148
	v_exp_f32_e32 v197, v149
	v_exp_f32_e32 v198, v150
	v_exp_f32_e32 v199, v151
	v_exp_f32_e32 v200, v152
	v_exp_f32_e32 v201, v153
	v_exp_f32_e32 v202, v154
	v_exp_f32_e32 v203, v155
	v_exp_f32_e32 v204, v156
	v_exp_f32_e32 v205, v157
	v_exp_f32_e32 v206, v158
	v_exp_f32_e32 v207, v159
	v_cvt_pk_bf16_f32 v230, v192, v193
	v_add_f32_e32 v3, v192, v194
	v_add_f32_e32 v7, v193, v195
	v_cvt_pk_bf16_f32 v231, v194, v195
	v_cvt_pk_bf16_f32 v232, v196, v197
	v_add_f32_e32 v3, v196, v3
	v_add_f32_e32 v7, v197, v7
	v_cvt_pk_bf16_f32 v233, v198, v199
	v_add_f32_e32 v3, v198, v3
	v_add_f32_e32 v7, v199, v7
	v_cvt_pk_bf16_f32 v234, v200, v201
	v_add_f32_e32 v3, v200, v3
	v_add_f32_e32 v7, v201, v7
	v_cvt_pk_bf16_f32 v235, v202, v203
	v_add_f32_e32 v3, v202, v3
	v_add_f32_e32 v7, v203, v7
	v_cvt_pk_bf16_f32 v236, v204, v205
	v_add_f32_e32 v3, v204, v3
	v_add_f32_e32 v7, v205, v7
	v_cvt_pk_bf16_f32 v237, v206, v207
	v_add_f32_e32 v3, v206, v3
	v_add_f32_e32 v7, v207, v7
	v_exp_f32_e32 v172, v112
	v_exp_f32_e32 v173, v113
	v_exp_f32_e32 v174, v114
	v_exp_f32_e32 v175, v115
	v_exp_f32_e32 v176, v116
	v_exp_f32_e32 v177, v117
	v_exp_f32_e32 v178, v118
	v_exp_f32_e32 v179, v119
	v_exp_f32_e32 v180, v120
	v_exp_f32_e32 v181, v121
	v_exp_f32_e32 v182, v122
	v_exp_f32_e32 v183, v123
	v_exp_f32_e32 v188, v124
	v_exp_f32_e32 v189, v125
	v_exp_f32_e32 v190, v126
	v_exp_f32_e32 v191, v127
	v_cvt_pk_bf16_f32 v238, v172, v173
	v_add_f32_e32 v4, v172, v174
	v_add_f32_e32 v8, v173, v175
	v_cvt_pk_bf16_f32 v239, v174, v175
	v_cvt_pk_bf16_f32 v240, v176, v177
	v_add_f32_e32 v4, v176, v4
	v_add_f32_e32 v8, v177, v8
	v_cvt_pk_bf16_f32 v241, v178, v179
	v_add_f32_e32 v4, v178, v4
	v_add_f32_e32 v8, v179, v8
	v_cvt_pk_bf16_f32 v242, v180, v181
	v_add_f32_e32 v4, v180, v4
	v_add_f32_e32 v8, v181, v8
	v_cvt_pk_bf16_f32 v243, v182, v183
	v_add_f32_e32 v4, v182, v4
	v_add_f32_e32 v8, v183, v8
	v_cvt_pk_bf16_f32 v244, v188, v189
	v_add_f32_e32 v4, v188, v4
	v_add_f32_e32 v8, v189, v8
	v_cvt_pk_bf16_f32 v245, v190, v191
	v_add_f32_e32 v4, v190, v4
	v_add_f32_e32 v8, v191, v8
	v_exp_f32_e32 v192, v96
	v_exp_f32_e32 v193, v97
	v_exp_f32_e32 v194, v98
	v_exp_f32_e32 v195, v99
	v_exp_f32_e32 v196, v100
	v_exp_f32_e32 v197, v101
	v_exp_f32_e32 v198, v102
	v_exp_f32_e32 v199, v103
	v_exp_f32_e32 v200, v104
	v_exp_f32_e32 v201, v105
	v_exp_f32_e32 v202, v106
	v_exp_f32_e32 v203, v107
	v_exp_f32_e32 v204, v108
	v_exp_f32_e32 v205, v109
	v_exp_f32_e32 v206, v110
	v_exp_f32_e32 v207, v111
	v_cvt_pk_bf16_f32 v246, v192, v193
	v_add_f32_e32 v5, v192, v194
	v_add_f32_e32 v9, v193, v195
	v_cvt_pk_bf16_f32 v247, v194, v195
	v_cvt_pk_bf16_f32 v248, v196, v197
	v_add_f32_e32 v5, v196, v5
	v_add_f32_e32 v9, v197, v9
	v_cvt_pk_bf16_f32 v249, v198, v199
	v_add_f32_e32 v5, v198, v5
	v_add_f32_e32 v9, v199, v9
	v_cvt_pk_bf16_f32 v216, v200, v201
	v_add_f32_e32 v5, v200, v5
	v_add_f32_e32 v9, v201, v9
	v_cvt_pk_bf16_f32 v217, v202, v203
	v_add_f32_e32 v5, v202, v5
	v_add_f32_e32 v9, v203, v9
	v_cvt_pk_bf16_f32 v218, v204, v205
	v_add_f32_e32 v5, v204, v5
	v_add_f32_e32 v9, v205, v9
	v_cvt_pk_bf16_f32 v219, v206, v207
	v_add_f32_e32 v5, v206, v5
	v_add_f32_e32 v9, v207, v9
	v_add_f32_e32 v2, v6, v2
	v_add_f32_e32 v3, v7, v3
	v_add_f32_e32 v4, v8, v4
	v_add_f32_e32 v5, v9, v5
	v_add_f32_e32 v2, v3, v2
	v_add_f32_e32 v4, v5, v4
	v_max_f32_e32 v6, v2, v4
	v_cmp_lt_f32_e32 vcc, 0x43800000, v6
	s_nop 0
	s_cbranch_vccnz .Lpb_slow

; #define LAS __attribute__((address_space(3)))
; template <int DV> ...
;     ...
;                 for (int d0 = 0; d0 < 4; ++d0) {
;                     kf[2 * d0] = *(const LAS bf16x8*)(Kl + (r32 * KP + 16 * d0 + 8 * hi) * 2);
;                     kf[2 * d0 + 1] = *(const LAS bf16x8*)(Kl + ((32 + r32) * KP + 16 * d0 + 8 * hi) * 2);
;                 }
;                 __builtin_amdgcn_sched_barrier(0);
;                 p0 = __builtin_amdgcn_mfma_f32_32x32x16_bf16(kf[0], qf[0], negm, 0, 0, 0); p1 = __builtin_amdgcn_mfma_f32_32x32x16_bf16(kf[1], qf[0], negm, 0, 0, 0);
; #pragma unroll
;                 for (int d0 = 1; d0 < 4; ++d0) { p0 = __builtin_amdgcn_mfma_f32_32x32x16_bf16(kf[2 * d0], qf[d0], p0, 0, 0, 0); p1 = __builtin_amdgcn_mfma_f32_32x32x16_bf16(kf[2 * d0 + 1], qf[d0], p1, 0, 0, 0); }
;     ...
;                         o[db] = __builtin_amdgcn_mfma_f32_32x32x16_bf16(vfa[db * 4 + c], pk[c], o[db], 0, 0, 0);
;                     }
;                 __builtin_amdgcn_sched_barrier(0);
; #pragma unroll
;                 for (int db = 2; db < DV / 32; ++db)
; #pragma unroll
;                     for (int c = 0; c < 4; ++c) {
;                         o[db] = __builtin_amdgcn_mfma_f32_32x32x16_bf16(vfb[(db - 2) * 4 + c], pk[c], o[db], 0, 0, 0);
;                     }
.Lpa_X2:
	s_setprio 1
	s_cmp_ge_i32 s22, s26
	s_cbranch_scc1 .Lpa_Xlast
	s_waitcnt lgkmcnt(11)
	v_mfma_f32_32x32x16_bf16 v[2:17], v[82:85], v[200:203], v[2:17]
	ds_read_b128 v[158:161], v197 offset:23040
	s_waitcnt lgkmcnt(11)
	v_mfma_f32_32x32x16_bf16 v[2:17], v[86:89], v[204:207], v[2:17]
	ds_read_b128 v[162:165], v197 offset:23072
	s_waitcnt lgkmcnt(11)
	v_mfma_f32_32x32x16_bf16 v[2:17], v[90:93], v[210:213], v[2:17]
	ds_read_b128 v[166:169], v197 offset:23104
	s_waitcnt lgkmcnt(11)
	v_mfma_f32_32x32x16_bf16 v[2:17], v[94:97], v[214:217], v[2:17]
	ds_read_b128 v[170:173], v197 offset:23136
	s_waitcnt vmcnt(0)
	s_waitcnt lgkmcnt(11)
	v_mfma_f32_32x32x16_bf16 v[18:33], v[98:101], v[200:203], v[18:33]
	ds_write_b128 v218, v[130:133]
	s_waitcnt lgkmcnt(11)
	v_mfma_f32_32x32x16_bf16 v[18:33], v[102:105], v[204:207], v[18:33]
	ds_write_b128 v219, v[134:137] offset:9216
	s_waitcnt lgkmcnt(11)
	v_mfma_f32_32x32x16_bf16 v[18:33], v[106:109], v[210:213], v[18:33]
	ds_write_b128 v219, v[138:141] offset:18432
	s_waitcnt lgkmcnt(11)
	v_mfma_f32_32x32x16_bf16 v[18:33], v[110:113], v[214:217], v[18:33]
	s_add_i32 s3, s22, 2
	s_add_i32 s4, s26, -1
	s_min_i32 s3, s3, s4
	s_cmp_lt_i32 s3, s1
	s_cselect_b32 s4, 0, s1
	s_cselect_b32 s5, s94, 0x2000
	s_sub_i32 s4, s3, s4
	s_lshl_b32 s4, s4, 6
	s_add_i32 s4, s5, s4
	s_ashr_i32 s5, s4, 31
	s_lshl_b64 s[30:31], s[4:5], 10
	v_lshl_add_u64 v[218:219], v[180:181], 0, s[30:31]
	s_lshl_b64 s[30:31], s[4:5], 1
	v_lshl_add_u64 v[220:221], v[182:183], 0, s[30:31]
	s_waitcnt lgkmcnt(10)
	v_mfma_f32_32x32x16_bf16 v[50:65], v[142:145], v[200:203], v[50:65]
	ds_read_b128 v[142:145], v199
	global_load_dwordx4 v[130:133], v[218:219], off
	s_waitcnt lgkmcnt(10)
	v_mfma_f32_32x32x16_bf16 v[50:65], v[146:149], v[204:207], v[50:65]
	ds_read_b128 v[146:149], v199 offset:4608
	global_load_dwordx4 v[134:137], v[220:221], off
	s_waitcnt lgkmcnt(10)
	v_mfma_f32_32x32x16_bf16 v[50:65], v[150:153], v[210:213], v[50:65]
	ds_read_b128 v[150:153], v199 offset:32
	v_lshl_add_u64 v[218:219], v[186:187], 0, s[30:31]
	s_waitcnt lgkmcnt(10)
	v_mfma_f32_32x32x16_bf16 v[50:65], v[154:157], v[214:217], v[50:65]
	ds_read_b128 v[154:157], v199 offset:4640
	global_load_dwordx4 v[138:141], v[218:219], off
	s_waitcnt lgkmcnt(10)
	v_mfma_f32_32x32x16_bf16 v[34:49], v[158:161], v[200:203], v[34:49]
	ds_read_b128 v[158:161], v199 offset:64
	s_waitcnt lgkmcnt(10)
	v_mfma_f32_32x32x16_bf16 v[34:49], v[162:165], v[204:207], v[34:49]
	ds_read_b128 v[162:165], v199 offset:4672
	s_waitcnt lgkmcnt(10)
	v_mfma_f32_32x32x16_bf16 v[34:49], v[166:169], v[210:213], v[34:49]
	ds_read_b128 v[166:169], v199 offset:96
	s_waitcnt lgkmcnt(10)
	v_mfma_f32_32x32x16_bf16 v[34:49], v[170:173], v[214:217], v[34:49]
	ds_read_b128 v[170:173], v199 offset:4704
	s_waitcnt lgkmcnt(7)
	v_mfma_f32_32x32x16_bf16 v[98:113], v[142:145], v[126:129], v[66:81]
	s_waitcnt lgkmcnt(5)
	v_mfma_f32_32x32x16_bf16 v[98:113], v[150:153], v[122:125], v[98:113]
	s_waitcnt lgkmcnt(3)
	v_mfma_f32_32x32x16_bf16 v[98:113], v[158:161], v[118:121], v[98:113]
	s_waitcnt lgkmcnt(1)
	v_mfma_f32_32x32x16_bf16 v[98:113], v[166:169], v[114:117], v[98:113]
	v_mfma_f32_32x32x16_bf16 v[82:97], v[146:149], v[126:129], v[66:81]
	v_mfma_f32_32x32x16_bf16 v[82:97], v[154:157], v[122:125], v[82:97]
	v_mfma_f32_32x32x16_bf16 v[82:97], v[162:165], v[118:121], v[82:97]
	s_waitcnt lgkmcnt(0)
	v_mfma_f32_32x32x16_bf16 v[82:97], v[170:173], v[114:117], v[82:97]
	s_barrier
	s_branch .Lpa_Y
.Lpa_Xfirst:
	ds_read_b128 v[142:145], v199
	ds_read_b128 v[146:149], v199 offset:4608
	ds_read_b128 v[150:153], v199 offset:32
	ds_read_b128 v[154:157], v199 offset:4640
	ds_read_b128 v[158:161], v199 offset:64
	ds_read_b128 v[162:165], v199 offset:4672
	ds_read_b128 v[166:169], v199 offset:96
	ds_read_b128 v[170:173], v199 offset:4704
	s_waitcnt lgkmcnt(7)
	v_mfma_f32_32x32x16_bf16 v[98:113], v[142:145], v[126:129], v[66:81]
	s_waitcnt lgkmcnt(5)
	v_mfma_f32_32x32x16_bf16 v[98:113], v[150:153], v[122:125], v[98:113]
	s_waitcnt lgkmcnt(3)
	v_mfma_f32_32x32x16_bf16 v[98:113], v[158:161], v[118:121], v[98:113]
	s_waitcnt lgkmcnt(1)
	v_mfma_f32_32x32x16_bf16 v[98:113], v[166:169], v[114:117], v[98:113]
	v_mfma_f32_32x32x16_bf16 v[82:97], v[146:149], v[126:129], v[66:81]
	v_mfma_f32_32x32x16_bf16 v[82:97], v[154:157], v[122:125], v[82:97]
	v_mfma_f32_32x32x16_bf16 v[82:97], v[162:165], v[118:121], v[82:97]
	s_waitcnt lgkmcnt(0)
	v_mfma_f32_32x32x16_bf16 v[82:97], v[170:173], v[114:117], v[82:97]
	s_waitcnt vmcnt(0)
	s_cmp_lt_i32 s26, 2
	s_cbranch_scc1 .Lpa_nokw
	ds_write_b128 v218, v[130:133]
	ds_write_b128 v219, v[134:137] offset:9216
	ds_write_b128 v219, v[138:141] offset:18432

; __device__ __forceinline__ unsigned cvtpk(float lo, float hi) { const f32x2_t v = {lo, hi}; const bf16x2_t b = __builtin_convertvector(v, bf16x2_t); return __builtin_bit_cast(unsigned, b); }
; template <int DV> ...
;     ...
;             float rs0 = 0.f, rs1 = 0.f;
; #pragma unroll
;             for (int r = 0; r < 16; ++r) { p0[r] = __builtin_amdgcn_exp2f(p0[r]); p1[r] = __builtin_amdgcn_exp2f(p1[r]); rs0 += p0[r]; rs1 += p1[r]; }
;             lrun += rs0 + rs1;
;             bf16x8 pk[4];
;             { u32x4 w;
;               w.x = cvtpk(p0[0], p0[1]); w.y = cvtpk(p0[2], p0[3]); w.z = cvtpk(p0[4], p0[5]); w.w = cvtpk(p0[6], p0[7]); pk[0] = __builtin_bit_cast(bf16x8, w);
;               w.x = cvtpk(p0[8], p0[9]); w.y = cvtpk(p0[10], p0[11]); w.z = cvtpk(p0[12], p0[13]); w.w = cvtpk(p0[14], p0[15]); pk[1] = __builtin_bit_cast(bf16x8, w);
;               w.x = cvtpk(p1[0], p1[1]); w.y = cvtpk(p1[2], p1[3]); w.z = cvtpk(p1[4], p1[5]); w.w = cvtpk(p1[6], p1[7]); pk[2] = __builtin_bit_cast(bf16x8, w);
;               w.x = cvtpk(p1[8], p1[9]); w.y = cvtpk(p1[10], p1[11]); w.z = cvtpk(p1[12], p1[13]); w.w = cvtpk(p1[14], p1[15]); pk[3] = __builtin_bit_cast(bf16x8, w); }
.Lpa_Y:
	s_setprio 0
	s_nop 1
	s_cmp_eq_u32 s22, 0
	s_cbranch_scc1 .Lpa_slow
	v_exp_f32_e32 v142, v98
	v_exp_f32_e32 v143, v99
	v_exp_f32_e32 v144, v100
	v_exp_f32_e32 v145, v101
	v_exp_f32_e32 v146, v102
	v_exp_f32_e32 v147, v103
	v_exp_f32_e32 v148, v104
	v_exp_f32_e32 v149, v105
	v_exp_f32_e32 v150, v106
	v_exp_f32_e32 v151, v107
	v_exp_f32_e32 v152, v108
	v_exp_f32_e32 v153, v109
	v_exp_f32_e32 v154, v110
	v_exp_f32_e32 v155, v111
	v_exp_f32_e32 v156, v112
	v_exp_f32_e32 v157, v113
	v_exp_f32_e32 v158, v82
	v_exp_f32_e32 v159, v83
	v_exp_f32_e32 v160, v84
	v_exp_f32_e32 v161, v85
	v_exp_f32_e32 v162, v86
	v_exp_f32_e32 v163, v87
	v_exp_f32_e32 v164, v88
	v_exp_f32_e32 v165, v89
	v_exp_f32_e32 v166, v90
	v_exp_f32_e32 v167, v91
	v_exp_f32_e32 v168, v92
	v_exp_f32_e32 v169, v93
	v_exp_f32_e32 v170, v94
	v_exp_f32_e32 v171, v95
	v_exp_f32_e32 v172, v96
	v_exp_f32_e32 v173, v97
	v_add_f32_e32 v198, v142, v143
	v_add_f32_e32 v199, v158, v159
	v_add_f32_e32 v198, v144, v198
	v_add_f32_e32 v199, v160, v199
	v_add_f32_e32 v198, v145, v198
	v_add_f32_e32 v199, v161, v199
	v_add_f32_e32 v198, v146, v198
	v_add_f32_e32 v199, v162, v199
	v_add_f32_e32 v198, v147, v198
	v_add_f32_e32 v199, v163, v199
	v_add_f32_e32 v198, v148, v198
	v_add_f32_e32 v199, v164, v199
	v_add_f32_e32 v198, v149, v198
	v_add_f32_e32 v199, v165, v199
	v_add_f32_e32 v198, v150, v198
	v_add_f32_e32 v199, v166, v199
	v_add_f32_e32 v198, v151, v198
	v_add_f32_e32 v199, v167, v199
	v_add_f32_e32 v198, v152, v198
	v_add_f32_e32 v199, v168, v199
	v_add_f32_e32 v198, v153, v198
	v_add_f32_e32 v199, v169, v199
	v_add_f32_e32 v198, v154, v198
	v_add_f32_e32 v199, v170, v199
	v_add_f32_e32 v198, v155, v198
	v_add_f32_e32 v199, v171, v199
	v_add_f32_e32 v198, v156, v198
	v_add_f32_e32 v199, v172, v199
	v_add_f32_e32 v198, v157, v198
	v_add_f32_e32 v199, v173, v199
	v_add_f32_e32 v198, v199, v198
	v_cmp_lt_f32_e32 vcc, 0x43800000, v198
	v_cvt_pk_bf16_f32 v200, v142, v143
	v_cvt_pk_bf16_f32 v201, v144, v145
	v_cvt_pk_bf16_f32 v202, v146, v147
	v_cvt_pk_bf16_f32 v203, v148, v149
	v_cvt_pk_bf16_f32 v204, v150, v151
	v_cvt_pk_bf16_f32 v205, v152, v153
	v_cvt_pk_bf16_f32 v206, v154, v155
	v_cvt_pk_bf16_f32 v207, v156, v157
	v_cvt_pk_bf16_f32 v210, v158, v159
	v_cvt_pk_bf16_f32 v211, v160, v161
	v_cvt_pk_bf16_f32 v212, v162, v163
	v_cvt_pk_bf16_f32 v213, v164, v165
	v_cvt_pk_bf16_f32 v214, v166, v167
	v_cvt_pk_bf16_f32 v215, v168, v169
	v_cvt_pk_bf16_f32 v216, v170, v171
	v_cvt_pk_bf16_f32 v217, v172, v173
	s_cbranch_vccnz .Lpa_slow
